# w_in projection phase also rewritten as 256x128 tiles (edge n-tile handled with a wave-column exec mask)
# speedup vs baseline: 1.0670x; 1.0107x over previous
; __device__ __forceinline__ int otid() { int t = threadIdx.x; asm volatile("" : "+v"(t)); return t; }
; __device__ __forceinline__ int frag_off(int fr, int fq) { return (fr >> 3) * 1024 + (fr & 7) * 128 + ((fq ^ ((fr >> 1) & 7)) << 4); }
;   const int tid = otid(), lane = tid & 63, wid = tid >> 6, wr = wid >> 1, wc = wid & 1, fr = lane & 15, fq = lane >> 4;
;   const int o0 = tid * 16;
;   const int lrow = (o0 >> 10) * 8 + ((o0 >> 7) & 7), lcol = ((((o0 >> 4) & 7) ^ ((lrow >> 1) & 7))) * 8;
;   const bf16_t* ag = A + (size_t)lrow * lda + lcol;
;   const bf16_t* bg = Bt + (size_t)lrow * ldb + lcol;
;   const char* A8 = (const char*)A;
;   const char* B8 = (const char*)Bt;
;   unsigned aoff[4], boff[NT];
; #pragma unroll
;   for (int i = 0; i < 4; ++i) aoff[i] = (unsigned)(((lrow + 32 * i) * lda + lcol) * 2);
; #pragma unroll
;   for (int i = 0; i < NT; ++i) boff[i] = (unsigned)(((lrow + (i & 1) * bs1 + (i >> 1) * bs2) * ldb + lcol) * 2);
;   const int wbase = __builtin_amdgcn_readfirstlane(wid) * 1024;
;   const int inner = frag_off(fr, fq);
;   const int abase = wr * 8192 + inner;
;   const int bbase = 16384 + wc * (NT * 2048) + inner;
; __device__ __forceinline__ void phase_win(const Params& p, char* smem, unsigned* tk) {
;     ...
;   for (TileIter ti(NTOK / 128, 25, 8, 5, tk); ti.valid();) {
;     int tm, tn; ti.get(tm, tn);
;     ti.prefetch();
;     f32x4 acc[4][4];
;     zero_acc<4>(acc);
;     gemm_main<4>(H + (size_t)tm * 128 * DM, DM, W + (size_t)tn * 128 * DM, DM, DM, acc, smem);
.LBB0_238:
	s_andn2_b64 vcc, exec, s[40:41]
	s_cbranch_vccnz .LBB0_285
	s_cmp_gt_i32 s77, 3
	s_mov_b64 s[34:35], -1
	s_cbranch_scc0 .LBB0_285
	v_readlane_b32 s30, v251, 11
	v_readlane_b32 s31, v251, 12
	v_mov_b32_e32 v0, v172
	s_andn2_b64 vcc, exec, s[30:31]
	s_cbranch_vccnz .LBB0_284
	s_lshl_b32 s98, s91, 3
	s_lshl_b64 s[34:35], s[98:99], 2
	v_readlane_b32 s23, v251, 3
	s_nop 1
	s_add_u32 s34, s23, s34
	v_readlane_b32 s23, v251, 4
	s_nop 1
	s_addc_u32 s35, s23, s35
	v_readlane_b32 s23, v251, 10
	s_nop 1
	s_lshr_b32 s23, s23, 1
	s_waitcnt vmcnt(0) lgkmcnt(0)
	v_readfirstlane_b32 s40, v92
	v_readfirstlane_b32 s41, v93
	v_readfirstlane_b32 s42, v94
	v_readfirstlane_b32 s43, v95
	v_readfirstlane_b32 s44, v96
	v_readfirstlane_b32 s45, v97
	v_readfirstlane_b32 s46, v98
	v_readfirstlane_b32 s47, v99
	v_writelane_b32 v249, s40, 0
	v_writelane_b32 v249, s41, 1
	v_writelane_b32 v249, s42, 2
	v_writelane_b32 v249, s43, 3
	v_writelane_b32 v249, s44, 4
	v_writelane_b32 v249, s45, 5
	v_writelane_b32 v249, s46, 6
	v_writelane_b32 v249, s47, 7
	v_readfirstlane_b32 s40, v100
	v_readfirstlane_b32 s41, v101
	v_readfirstlane_b32 s42, v102
	v_readfirstlane_b32 s43, v103
	v_readfirstlane_b32 s44, v104
	v_readfirstlane_b32 s45, v105
	v_readfirstlane_b32 s46, v106
	v_readfirstlane_b32 s47, v107
	v_writelane_b32 v249, s40, 8
	v_writelane_b32 v249, s41, 9
	v_writelane_b32 v249, s42, 10
	v_writelane_b32 v249, s43, 11
	v_writelane_b32 v249, s44, 12
	v_writelane_b32 v249, s45, 13
	v_writelane_b32 v249, s46, 14
	v_writelane_b32 v249, s47, 15
	v_readfirstlane_b32 s40, v108
	v_readfirstlane_b32 s41, v109
	v_readfirstlane_b32 s42, v110
	v_readfirstlane_b32 s43, v111
	v_readfirstlane_b32 s44, v112
	v_readfirstlane_b32 s45, v113
	v_readfirstlane_b32 s46, v114
	v_readfirstlane_b32 s47, v115
	v_writelane_b32 v249, s40, 16
	v_writelane_b32 v249, s41, 17
	v_writelane_b32 v249, s42, 18
	v_writelane_b32 v249, s43, 19
	v_writelane_b32 v249, s44, 20
	v_writelane_b32 v249, s45, 21
	v_writelane_b32 v249, s46, 22
	v_writelane_b32 v249, s47, 23
	v_readfirstlane_b32 s40, v116
	v_readfirstlane_b32 s41, v117
	v_readfirstlane_b32 s42, v118
	v_readfirstlane_b32 s43, v119
	v_readfirstlane_b32 s44, v120
	v_readfirstlane_b32 s45, v121
	v_readfirstlane_b32 s46, v122
	v_readfirstlane_b32 s47, v123
	v_writelane_b32 v249, s40, 24
	v_writelane_b32 v249, s41, 25
	v_writelane_b32 v249, s42, 26
	v_writelane_b32 v249, s43, 27
	v_writelane_b32 v249, s44, 28
	v_writelane_b32 v249, s45, 29
	v_writelane_b32 v249, s46, 30
	v_writelane_b32 v249, s47, 31
	v_readfirstlane_b32 s40, v124
	v_readfirstlane_b32 s41, v125
	v_readfirstlane_b32 s42, v126
	v_readfirstlane_b32 s43, v127
	v_readfirstlane_b32 s44, v128
	v_readfirstlane_b32 s45, v129
	v_readfirstlane_b32 s46, v130
	v_readfirstlane_b32 s47, v131
	v_writelane_b32 v249, s40, 32
	v_writelane_b32 v249, s41, 33
	v_writelane_b32 v249, s42, 34
	v_writelane_b32 v249, s43, 35
	v_writelane_b32 v249, s44, 36
	v_writelane_b32 v249, s45, 37
	v_writelane_b32 v249, s46, 38
	v_writelane_b32 v249, s47, 39
	v_readfirstlane_b32 s40, v132
	v_readfirstlane_b32 s41, v133
	s_nop 1
	v_writelane_b32 v249, s40, 40
	v_writelane_b32 v249, s41, 41
	v_readfirstlane_b32 s100, v90
	v_readfirstlane_b32 s101, v91
	v_lshrrev_b32_e32 v238, 4, v172
	v_and_b32_e32 v238, 7, v238
	v_and_b32_e32 v239, 7, v172
	v_xor_b32_e32 v238, v238, v239
	v_lshlrev_b32_e32 v238, 4, v238
	v_lshrrev_b32_e32 v239, 3, v172
	v_lshl_or_b32 v228, v239, 11, v238
	v_and_b32_e32 v238, 15, v172
	v_lshrrev_b32_e32 v239, 1, v238
	v_and_b32_e32 v239, 7, v239
	v_bfe_u32 v240, v172, 4, 2
	v_xor_b32_e32 v239, v239, v240
	v_lshlrev_b32_e32 v239, 4, v239
	v_and_b32_e32 v240, 7, v238
	v_lshl_or_b32 v239, v240, 7, v239
	v_lshrrev_b32_e32 v240, 3, v238
	v_lshl_or_b32 v239, v240, 10, v239
	v_lshrrev_b32_e32 v240, 7, v172
	v_lshl_or_b32 v231, v240, 14, v239
	v_bfe_u32 v240, v172, 6, 1
	v_lshl_or_b32 v232, v240, 13, v239
	v_add_u32_e32 v232, 0x10000, v232
	v_xor_b32_e32 v235, 64, v231
	v_xor_b32_e32 v236, 64, v232
	v_readfirstlane_b32 s46, v172
	s_nop 3
	s_lshr_b32 s46, s46, 6
	s_lshl_b32 s46, s46, 10
	v_lshrrev_b32_e32 v238, 7, v172
	v_and_b32_e32 v239, 15, v172
	v_lshl_or_b32 v238, v238, 7, v239
	v_bfe_u32 v239, v172, 6, 1
	v_bfe_u32 v240, v172, 4, 2
	v_lshlrev_b32_e32 v240, 3, v240
	v_lshl_or_b32 v239, v239, 7, v240
	s_movk_i32 s45, 0x1820
	v_mad_u32_u24 v234, v238, s45, v239
	s_mov_b32 s44, s39
;     ...
;   const int nk = K >> 6;
; #pragma unroll
;   for (int i = 0; i < 4; ++i) __builtin_amdgcn_global_load_lds((const unsigned*)(ag + (size_t)(32 * i) * lda), (unsigned*)(smem + i * 4096 + o0), 16, 0, 0);
; #pragma unroll
;   for (int i = 0; i < NT; ++i) __builtin_amdgcn_global_load_lds((const unsigned*)(bg + (size_t)((i & 1) * bs1 + (i >> 1) * bs2) * ldb), (unsigned*)(smem + 16384 + i * 4096 + o0), 16, 0, 0);
;   asm volatile("s_waitcnt vmcnt(0)" ::: "memory");
;   __syncthreads();
; __device__ __forceinline__ void phase_win(const Params& p, char* smem, unsigned* tk) {
;     ...
;   for (TileIter ti(NTOK / 128, 25, 8, 5, tk); ti.valid();) {
;     int tm, tn; ti.get(tm, tn);
;     ti.prefetch();
;     f32x4 acc[4][4];
;     zero_acc<4>(acc);
;     gemm_main<4>(H + (size_t)tm * 128 * DM, DM, W + (size_t)tn * 128 * DM, DM, DM, acc, smem);
.Lwn_tile:
	s_cmp_ge_u32 s44, s23
	s_cbranch_scc1 .Lwn_exit
	s_and_saveexec_b64 s[48:49], s[62:63]
	s_cbranch_execz .Lwn_tk0
	v_mov_b32_e32 v0, 1
	global_atomic_add v233, v1, v0, s[34:35] sc0
.Lwn_tk0:
	s_or_b64 exec, exec, s[48:49]
	s_mul_i32 s45, s44, 3277
	s_lshr_b32 s45, s45, 16
	s_mul_i32 s48, s45, 20
	s_sub_i32 s48, s44, s48
	s_lshl_b32 s45, s45, 3
	s_add_i32 s45, s45, s72
	s_mul_i32 s47, s45, 13108
	s_lshr_b32 s47, s47, 16
	s_mul_i32 s49, s47, 5
	s_sub_i32 s45, s45, s49
	s_mul_i32 s49, s48, 13108
	s_lshr_b32 s49, s49, 16
	s_lshl_b32 s47, s47, 2
	s_add_i32 s47, s47, s49
	s_mul_i32 s49, s49, 5
	s_sub_i32 s48, s48, s49
	s_mul_i32 s45, s45, 5
	s_add_i32 s98, s45, s48
	s_lshl_b32 s45, s47, 19
	s_add_u32 s40, s100, s45
	s_addc_u32 s41, s101, 0
	s_add_u32 s40, s40, 0x4380000
	s_addc_u32 s41, s41, 0
	s_lshl_b32 s48, s98, 18
	s_add_u32 s42, s100, s48
	s_addc_u32 s43, s101, 0
	s_add_u32 s42, s42, 0x2100000
	s_addc_u32 s43, s43, 0
	s_add_i32 m0, s46, 0x0
	s_nop 0
	global_load_lds_dwordx4 v228, s[40:41]
	v_add_u32_e32 v230, 0x10000, v228
	s_add_i32 m0, s46, 0x1000
	s_nop 0
	global_load_lds_dwordx4 v230, s[40:41]
	v_add_u32_e32 v230, 0x20000, v228
	s_add_i32 m0, s46, 0x2000
	s_nop 0
	global_load_lds_dwordx4 v230, s[40:41]
	v_add_u32_e32 v230, 0x30000, v228
	s_add_i32 m0, s46, 0x3000
	s_nop 0
	global_load_lds_dwordx4 v230, s[40:41]
	v_add_u32_e32 v230, 0x40000, v228
	s_add_i32 m0, s46, 0x4000
	s_nop 0
	global_load_lds_dwordx4 v230, s[40:41]
	v_add_u32_e32 v230, 0x50000, v228
	s_add_i32 m0, s46, 0x5000
	s_nop 0
	global_load_lds_dwordx4 v230, s[40:41]
	v_add_u32_e32 v230, 0x60000, v228
	s_add_i32 m0, s46, 0x6000
	s_nop 0
	global_load_lds_dwordx4 v230, s[40:41]
	v_add_u32_e32 v230, 0x70000, v228
	s_add_i32 m0, s46, 0x7000
	s_nop 0
	global_load_lds_dwordx4 v230, s[40:41]
	s_add_i32 m0, s46, 0x10000
	s_nop 0
	global_load_lds_dwordx4 v228, s[42:43]
	v_add_u32_e32 v230, 0x10000, v228
	s_add_i32 m0, s46, 0x11000
	s_nop 0
	global_load_lds_dwordx4 v230, s[42:43]
	v_add_u32_e32 v230, 0x20000, v228
	s_add_i32 m0, s46, 0x12000
	s_nop 0
	global_load_lds_dwordx4 v230, s[42:43]
	v_add_u32_e32 v230, 0x30000, v228
	s_add_i32 m0, s46, 0x13000
	s_nop 0
	global_load_lds_dwordx4 v230, s[42:43]
	v_mov_b64_e32 v[2:3], 0
	v_mov_b64_e32 v[4:5], 0
	v_mov_b64_e32 v[6:7], 0
	v_mov_b64_e32 v[8:9], 0
	v_mov_b64_e32 v[10:11], 0
	v_mov_b64_e32 v[12:13], 0
	v_mov_b64_e32 v[14:15], 0
	v_mov_b64_e32 v[16:17], 0
	v_mov_b64_e32 v[18:19], 0
	v_mov_b64_e32 v[20:21], 0
	v_mov_b64_e32 v[22:23], 0
	v_mov_b64_e32 v[24:25], 0
	v_mov_b64_e32 v[26:27], 0
	v_mov_b64_e32 v[28:29], 0
	v_mov_b64_e32 v[30:31], 0
	v_mov_b64_e32 v[32:33], 0
	v_mov_b64_e32 v[34:35], 0
	v_mov_b64_e32 v[36:37], 0
	v_mov_b64_e32 v[38:39], 0
	v_mov_b64_e32 v[40:41], 0
	v_mov_b64_e32 v[42:43], 0
	v_mov_b64_e32 v[44:45], 0
	v_mov_b64_e32 v[46:47], 0
	v_mov_b64_e32 v[48:49], 0
	v_mov_b64_e32 v[50:51], 0
	v_mov_b64_e32 v[52:53], 0
	v_mov_b64_e32 v[54:55], 0
	v_mov_b64_e32 v[56:57], 0
	v_mov_b64_e32 v[58:59], 0
	v_mov_b64_e32 v[60:61], 0
	v_mov_b64_e32 v[62:63], 0
	v_mov_b64_e32 v[64:65], 0
	v_mov_b64_e32 v[66:67], 0
	v_mov_b64_e32 v[68:69], 0
	v_mov_b64_e32 v[70:71], 0
	v_mov_b64_e32 v[72:73], 0
	v_mov_b64_e32 v[74:75], 0
	v_mov_b64_e32 v[76:77], 0
	v_mov_b64_e32 v[78:79], 0
	v_mov_b64_e32 v[80:81], 0
	v_mov_b64_e32 v[82:83], 0
	v_mov_b64_e32 v[84:85], 0
	v_mov_b64_e32 v[86:87], 0
	v_mov_b64_e32 v[88:89], 0
	v_mov_b64_e32 v[92:93], 0
	v_mov_b64_e32 v[94:95], 0
	v_mov_b64_e32 v[96:97], 0
	v_mov_b64_e32 v[98:99], 0
	v_mov_b64_e32 v[100:101], 0
	v_mov_b64_e32 v[102:103], 0
	v_mov_b64_e32 v[104:105], 0
	v_mov_b64_e32 v[106:107], 0
	v_mov_b64_e32 v[108:109], 0
	v_mov_b64_e32 v[110:111], 0
	v_mov_b64_e32 v[112:113], 0
	v_mov_b64_e32 v[114:115], 0
	v_mov_b64_e32 v[116:117], 0
	v_mov_b64_e32 v[118:119], 0
	v_mov_b64_e32 v[120:121], 0
	v_mov_b64_e32 v[122:123], 0
	v_mov_b64_e32 v[124:125], 0
	v_mov_b64_e32 v[126:127], 0
	v_mov_b64_e32 v[128:129], 0
	v_mov_b64_e32 v[130:131], 0
	s_waitcnt vmcnt(0)
	s_barrier
	s_mov_b32 s45, 7

; __device__ __forceinline__ void phase_win(const Params& p, char* smem, unsigned* tk) {
;     ...
;     ti.next(smem);
;     const int col0 = tn * 128 + wc * 64 + fq * 4;
;     bf16_t* ob = P + (size_t)(tm * 128 + wr * 64 + fr) * PC + col0;
; #pragma unroll
;     for (int m = 0; m < 4; ++m) {
; #pragma unroll
;       for (int n = 0; n < 4; ++n) {
;         if (col0 + n * 16 < PC) {
;           u32x2 pk; pk.x = pack2(acc[m][n][0], acc[m][n][1]); pk.y = pack2(acc[m][n][2], acc[m][n][3]);
;           *(u32x2*)(ob + (m * 16) * PC + n * 16) = pk;
;         }
;       }
;       __builtin_amdgcn_sched_barrier(0);
;     }
.Lwn_tk1:
	s_or_b64 exec, exec, s[48:49]
	s_waitcnt lgkmcnt(0)
	s_barrier
	ds_read_b32 v0, v1
	s_waitcnt lgkmcnt(0)
	v_readfirstlane_b32 s44, v0
	s_barrier
	s_mul_i32 s45, s47, 0x182000
	s_add_u32 s48, s100, s45
	s_addc_u32 s49, s101, 0
	s_add_u32 s48, s48, 0x8b80000
	s_addc_u32 s49, s49, 0
	s_lshl_b32 s45, s98, 8
	s_add_u32 s48, s48, s45
	s_addc_u32 s49, s49, 0
	s_cmp_eq_u32 s98, 24
	s_cbranch_scc1 .Lwn_edge
	v_cvt_pk_bf16_f32 v2, v2, v3
	v_cvt_pk_bf16_f32 v3, v4, v5
	global_store_dwordx2 v234, v[2:3], s[48:49]
	v_cvt_pk_bf16_f32 v6, v6, v7
	v_cvt_pk_bf16_f32 v7, v8, v9
	global_store_dwordx2 v234, v[6:7], s[48:49] offset:32
	v_cvt_pk_bf16_f32 v10, v10, v11
	v_cvt_pk_bf16_f32 v11, v12, v13
	global_store_dwordx2 v234, v[10:11], s[48:49] offset:64
	v_cvt_pk_bf16_f32 v14, v14, v15
	v_cvt_pk_bf16_f32 v15, v16, v17
	global_store_dwordx2 v234, v[14:15], s[48:49] offset:96
	s_add_u32 s48, s48, 0x18200
	s_addc_u32 s49, s49, 0
	v_cvt_pk_bf16_f32 v18, v18, v19
	v_cvt_pk_bf16_f32 v19, v20, v21
	global_store_dwordx2 v234, v[18:19], s[48:49]
	v_cvt_pk_bf16_f32 v22, v22, v23
	v_cvt_pk_bf16_f32 v23, v24, v25
	global_store_dwordx2 v234, v[22:23], s[48:49] offset:32
	v_cvt_pk_bf16_f32 v26, v26, v27
	v_cvt_pk_bf16_f32 v27, v28, v29
	global_store_dwordx2 v234, v[26:27], s[48:49] offset:64
	v_cvt_pk_bf16_f32 v30, v30, v31
	v_cvt_pk_bf16_f32 v31, v32, v33
	global_store_dwordx2 v234, v[30:31], s[48:49] offset:96
	s_add_u32 s48, s48, 0x18200
	s_addc_u32 s49, s49, 0
	v_cvt_pk_bf16_f32 v34, v34, v35
	v_cvt_pk_bf16_f32 v35, v36, v37
	global_store_dwordx2 v234, v[34:35], s[48:49]
	v_cvt_pk_bf16_f32 v38, v38, v39
	v_cvt_pk_bf16_f32 v39, v40, v41
	global_store_dwordx2 v234, v[38:39], s[48:49] offset:32
	v_cvt_pk_bf16_f32 v42, v42, v43
	v_cvt_pk_bf16_f32 v43, v44, v45
	global_store_dwordx2 v234, v[42:43], s[48:49] offset:64
	v_cvt_pk_bf16_f32 v46, v46, v47
	v_cvt_pk_bf16_f32 v47, v48, v49
	global_store_dwordx2 v234, v[46:47], s[48:49] offset:96
	s_add_u32 s48, s48, 0x18200
	s_addc_u32 s49, s49, 0
	v_cvt_pk_bf16_f32 v50, v50, v51
	v_cvt_pk_bf16_f32 v51, v52, v53
	global_store_dwordx2 v234, v[50:51], s[48:49]
	v_cvt_pk_bf16_f32 v54, v54, v55
	v_cvt_pk_bf16_f32 v55, v56, v57
	global_store_dwordx2 v234, v[54:55], s[48:49] offset:32
	v_cvt_pk_bf16_f32 v58, v58, v59
	v_cvt_pk_bf16_f32 v59, v60, v61
	global_store_dwordx2 v234, v[58:59], s[48:49] offset:64
	v_cvt_pk_bf16_f32 v62, v62, v63
	v_cvt_pk_bf16_f32 v63, v64, v65
	global_store_dwordx2 v234, v[62:63], s[48:49] offset:96
	s_add_u32 s48, s48, 0x18200
	s_addc_u32 s49, s49, 0
	v_cvt_pk_bf16_f32 v66, v66, v67
	v_cvt_pk_bf16_f32 v67, v68, v69
	global_store_dwordx2 v234, v[66:67], s[48:49]
	v_cvt_pk_bf16_f32 v70, v70, v71
	v_cvt_pk_bf16_f32 v71, v72, v73
	global_store_dwordx2 v234, v[70:71], s[48:49] offset:32
	v_cvt_pk_bf16_f32 v74, v74, v75
	v_cvt_pk_bf16_f32 v75, v76, v77
	global_store_dwordx2 v234, v[74:75], s[48:49] offset:64
	v_cvt_pk_bf16_f32 v78, v78, v79
	v_cvt_pk_bf16_f32 v79, v80, v81
	global_store_dwordx2 v234, v[78:79], s[48:49] offset:96
	s_add_u32 s48, s48, 0x18200
	s_addc_u32 s49, s49, 0
	v_cvt_pk_bf16_f32 v82, v82, v83
	v_cvt_pk_bf16_f32 v83, v84, v85
	global_store_dwordx2 v234, v[82:83], s[48:49]
	v_cvt_pk_bf16_f32 v86, v86, v87
	v_cvt_pk_bf16_f32 v87, v88, v89
	global_store_dwordx2 v234, v[86:87], s[48:49] offset:32
	v_cvt_pk_bf16_f32 v92, v92, v93
	v_cvt_pk_bf16_f32 v93, v94, v95
	global_store_dwordx2 v234, v[92:93], s[48:49] offset:64
	v_cvt_pk_bf16_f32 v96, v96, v97
	v_cvt_pk_bf16_f32 v97, v98, v99
	global_store_dwordx2 v234, v[96:97], s[48:49] offset:96
	s_add_u32 s48, s48, 0x18200
	s_addc_u32 s49, s49, 0
	v_cvt_pk_bf16_f32 v100, v100, v101
	v_cvt_pk_bf16_f32 v101, v102, v103
	global_store_dwordx2 v234, v[100:101], s[48:49]
	v_cvt_pk_bf16_f32 v104, v104, v105
	v_cvt_pk_bf16_f32 v105, v106, v107
	global_store_dwordx2 v234, v[104:105], s[48:49] offset:32
	v_cvt_pk_bf16_f32 v108, v108, v109
	v_cvt_pk_bf16_f32 v109, v110, v111
	global_store_dwordx2 v234, v[108:109], s[48:49] offset:64
	v_cvt_pk_bf16_f32 v112, v112, v113
	v_cvt_pk_bf16_f32 v113, v114, v115
	global_store_dwordx2 v234, v[112:113], s[48:49] offset:96
	s_add_u32 s48, s48, 0x18200
	s_addc_u32 s49, s49, 0
	v_cvt_pk_bf16_f32 v116, v116, v117
	v_cvt_pk_bf16_f32 v117, v118, v119
	global_store_dwordx2 v234, v[116:117], s[48:49]
	v_cvt_pk_bf16_f32 v120, v120, v121
	v_cvt_pk_bf16_f32 v121, v122, v123
	global_store_dwordx2 v234, v[120:121], s[48:49] offset:32
	v_cvt_pk_bf16_f32 v124, v124, v125
	v_cvt_pk_bf16_f32 v125, v126, v127
	global_store_dwordx2 v234, v[124:125], s[48:49] offset:64
	v_cvt_pk_bf16_f32 v128, v128, v129
	v_cvt_pk_bf16_f32 v129, v130, v131
	global_store_dwordx2 v234, v[128:129], s[48:49] offset:96
	s_branch .Lwn_epi_done
; __device__ __forceinline__ void phase_win(const Params& p, char* smem, unsigned* tk) {
;     ...
;     const int col0 = tn * 128 + wc * 64 + fq * 4;
;     bf16_t* ob = P + (size_t)(tm * 128 + wr * 64 + fr) * PC + col0;
; #pragma unroll
;     for (int m = 0; m < 4; ++m) {
; #pragma unroll
;       for (int n = 0; n < 4; ++n) {
;         if (col0 + n * 16 < PC) {
;           u32x2 pk; pk.x = pack2(acc[m][n][0], acc[m][n][1]); pk.y = pack2(acc[m][n][2], acc[m][n][3]);
;           *(u32x2*)(ob + (m * 16) * PC + n * 16) = pk;
;         }
;       }
;       __builtin_amdgcn_sched_barrier(0);
;     }
.Lwn_edge:
	v_bfe_u32 v0, v172, 6, 1
	v_cmp_eq_u32_e32 vcc, 0, v0
	s_and_saveexec_b64 s[50:51], vcc
	s_cbranch_execz .Lwn_edge_done
	v_cvt_pk_bf16_f32 v2, v2, v3
	v_cvt_pk_bf16_f32 v3, v4, v5
	global_store_dwordx2 v234, v[2:3], s[48:49]
	s_add_u32 s48, s48, 0x18200
	s_addc_u32 s49, s49, 0
	v_cvt_pk_bf16_f32 v18, v18, v19
	v_cvt_pk_bf16_f32 v19, v20, v21
	global_store_dwordx2 v234, v[18:19], s[48:49]
	s_add_u32 s48, s48, 0x18200
	s_addc_u32 s49, s49, 0
	v_cvt_pk_bf16_f32 v34, v34, v35
	v_cvt_pk_bf16_f32 v35, v36, v37
	global_store_dwordx2 v234, v[34:35], s[48:49]
	s_add_u32 s48, s48, 0x18200
	s_addc_u32 s49, s49, 0
	v_cvt_pk_bf16_f32 v50, v50, v51
	v_cvt_pk_bf16_f32 v51, v52, v53
	global_store_dwordx2 v234, v[50:51], s[48:49]
	s_add_u32 s48, s48, 0x18200
	s_addc_u32 s49, s49, 0
	v_cvt_pk_bf16_f32 v66, v66, v67
	v_cvt_pk_bf16_f32 v67, v68, v69
	global_store_dwordx2 v234, v[66:67], s[48:49]
	s_add_u32 s48, s48, 0x18200
	s_addc_u32 s49, s49, 0
	v_cvt_pk_bf16_f32 v82, v82, v83
	v_cvt_pk_bf16_f32 v83, v84, v85
	global_store_dwordx2 v234, v[82:83], s[48:49]
	s_add_u32 s48, s48, 0x18200
	s_addc_u32 s49, s49, 0
	v_cvt_pk_bf16_f32 v100, v100, v101
	v_cvt_pk_bf16_f32 v101, v102, v103
	global_store_dwordx2 v234, v[100:101], s[48:49]
	s_add_u32 s48, s48, 0x18200
	s_addc_u32 s49, s49, 0
	v_cvt_pk_bf16_f32 v116, v116, v117
	v_cvt_pk_bf16_f32 v117, v118, v119
	global_store_dwordx2 v234, v[116:117], s[48:49]
.Lwn_edge_done:
	s_or_b64 exec, exec, s[50:51]
.Lwn_epi_done:
	s_branch .Lwn_tile
.Lwn_exit:
	s_waitcnt vmcnt(0) lgkmcnt(0)
	v_readlane_b32 s40, v249, 0
	v_readlane_b32 s41, v249, 1
	v_readlane_b32 s42, v249, 2
	v_readlane_b32 s43, v249, 3
	v_readlane_b32 s44, v249, 4
	v_readlane_b32 s45, v249, 5
	v_readlane_b32 s46, v249, 6
	v_readlane_b32 s47, v249, 7
	v_mov_b32_e32 v92, s40
	v_mov_b32_e32 v93, s41
	v_mov_b32_e32 v94, s42
	v_mov_b32_e32 v95, s43
	v_mov_b32_e32 v96, s44
	v_mov_b32_e32 v97, s45
	v_mov_b32_e32 v98, s46
	v_mov_b32_e32 v99, s47
	v_readlane_b32 s40, v249, 8
	v_readlane_b32 s41, v249, 9
	v_readlane_b32 s42, v249, 10
	v_readlane_b32 s43, v249, 11
	v_readlane_b32 s44, v249, 12
	v_readlane_b32 s45, v249, 13
	v_readlane_b32 s46, v249, 14
	v_readlane_b32 s47, v249, 15
	v_mov_b32_e32 v100, s40
	v_mov_b32_e32 v101, s41
	v_mov_b32_e32 v102, s42
	v_mov_b32_e32 v103, s43
	v_mov_b32_e32 v104, s44
	v_mov_b32_e32 v105, s45
	v_mov_b32_e32 v106, s46
	v_mov_b32_e32 v107, s47
	v_readlane_b32 s40, v249, 16
	v_readlane_b32 s41, v249, 17
	v_readlane_b32 s42, v249, 18
	v_readlane_b32 s43, v249, 19
	v_readlane_b32 s44, v249, 20
	v_readlane_b32 s45, v249, 21
	v_readlane_b32 s46, v249, 22
	v_readlane_b32 s47, v249, 23
	v_mov_b32_e32 v108, s40
	v_mov_b32_e32 v109, s41
	v_mov_b32_e32 v110, s42
	v_mov_b32_e32 v111, s43
	v_mov_b32_e32 v112, s44
	v_mov_b32_e32 v113, s45
	v_mov_b32_e32 v114, s46
	v_mov_b32_e32 v115, s47
	v_readlane_b32 s40, v249, 24
	v_readlane_b32 s41, v249, 25
	v_readlane_b32 s42, v249, 26
	v_readlane_b32 s43, v249, 27
	v_readlane_b32 s44, v249, 28
	v_readlane_b32 s45, v249, 29
	v_readlane_b32 s46, v249, 30
	v_readlane_b32 s47, v249, 31
	v_mov_b32_e32 v116, s40
	v_mov_b32_e32 v117, s41
	v_mov_b32_e32 v118, s42
	v_mov_b32_e32 v119, s43
	v_mov_b32_e32 v120, s44
	v_mov_b32_e32 v121, s45
	v_mov_b32_e32 v122, s46
	v_mov_b32_e32 v123, s47
	v_readlane_b32 s40, v249, 32
	v_readlane_b32 s41, v249, 33
	v_readlane_b32 s42, v249, 34
	v_readlane_b32 s43, v249, 35
	v_readlane_b32 s44, v249, 36
	v_readlane_b32 s45, v249, 37
	v_readlane_b32 s46, v249, 38
	v_readlane_b32 s47, v249, 39
	v_mov_b32_e32 v124, s40
	v_mov_b32_e32 v125, s41
	v_mov_b32_e32 v126, s42
	v_mov_b32_e32 v127, s43
	v_mov_b32_e32 v128, s44
	v_mov_b32_e32 v129, s45
	v_mov_b32_e32 v130, s46
	v_mov_b32_e32 v131, s47
	v_readlane_b32 s40, v249, 40
	v_readlane_b32 s41, v249, 41
	s_nop 1
	v_mov_b32_e32 v132, s40
	v_mov_b32_e32 v133, s41
.LBB0_284:
	s_mov_b64 s[34:35], 0
